# attention: static setprio 1 for waves 4-7
# baseline (speedup 1.0000x reference)
.LBB0_1051:
	s_or_b64 exec, exec, s[4:5]
	s_mov_b64 s[12:13], s[0:1]
	s_waitcnt lgkmcnt(0)
	s_barrier
	s_cmp_lt_u32 s33, 0x100
	s_cbranch_scc1 .Latt_prio_skip
	s_setprio 1
.Latt_prio_skip:
	s_mov_b32 s17, s2
	s_load_dwordx2 s[8:9], s[12:13], 0xa0
	v_mbcnt_lo_u32_b32 v4, -1, 0
	v_mbcnt_hi_u32_b32 v4, -1, v4
	s_load_dwordx4 s[4:7], s[12:13], 0x68
	s_load_dwordx2 s[14:15], s[12:13], 0x50
	v_and_b32_e32 v0, 63, v4
	v_lshlrev_b32_e32 v1, 2, v0
	s_waitcnt lgkmcnt(0)
	global_load_dword v7, v1, s[4:5]
	global_load_dword v6, v1, s[14:15]
	s_ashr_i32 s18, s17, 4
	s_mul_i32 s4, s18, 0x201
	v_mov_b32_e32 v1, 0
	s_ashr_i32 s5, s4, 31
	v_add_u32_e32 v5, s33, v4
	v_lshl_add_u64 v[2:3], s[4:5], 0, v[0:1]
	v_readfirstlane_b32 s16, v5
	v_or_b32_e32 v8, 0xffffffc0, v0
	v_lshl_add_u64 v[2:3], v[2:3], 2, s[6:7]
	v_mov_b32_e32 v1, 0xf149f2ca
	s_mov_b64 s[12:13], 0
	s_mov_b64 s[14:15], 0x100
	s_movk_i32 s5, 0x1c0
	global_load_dword v9, v[2:3], off
	global_load_dword v10, v[2:3], off offset:256
	global_load_dword v11, v[2:3], off offset:512
	global_load_dword v12, v[2:3], off offset:768
	global_load_dword v13, v[2:3], off offset:1024
	global_load_dword v14, v[2:3], off offset:1280
	global_load_dword v15, v[2:3], off offset:1536
	global_load_dword v16, v[2:3], off offset:1792
	v_mov_b32_e32 v17, 0xf149f2ca
	v_cmp_eq_u32_e32 vcc, 0, v0
	s_and_saveexec_b64 s[12:13], vcc
	global_load_dword v17, v[2:3], off offset:2048
	s_or_b64 exec, exec, s[12:13]
	s_waitcnt vmcnt(0)
	v_max3_f32 v1, v9, v10, v11
	v_max3_f32 v1, v1, v12, v13
	v_max3_f32 v1, v1, v14, v15
	v_max3_f32 v1, v1, v16, v17
	v_max_f32_e32 v1, 0xf149f2ca, v1

.LBB0_1075:
	s_setprio 0
	s_waitcnt vmcnt(0)
	s_barrier
	s_and_saveexec_b64 s[4:5], s[10:11]
	s_cbranch_execz .LBB0_1127
	s_add_i32 s6, 0, 0x20160
	v_mov_b32_e32 v0, s6
	s_waitcnt vmcnt(0) expcnt(0) lgkmcnt(0)
	s_cmp_eq_u32 s98, 0
	s_cbranch_scc1 .Leinv_8
	buffer_inv sc1
